# p[l] f32->bf16 conversion loops: 4 iterations per pass with 8 loads in flight per lane and counted waits (both call sites)
# speedup vs baseline: 1.0014x; 1.0014x over previous
.LBB0_106:
	v_ashrrev_i32_e32 v7, 31, v6
	v_lshl_add_u64 v[18:19], v[6:7], 4, s[0:1]
	global_load_dwordx4 v[168:171], v[18:19], off nt
	global_load_dwordx4 v[176:179], v[18:19], off offset:16 nt
	v_add_u32_e32 v8, s4, v8
	v_add_u32_e32 v6, s5, v6
	v_ashrrev_i32_e32 v7, 31, v6
	v_lshl_add_u64 v[18:19], v[6:7], 4, s[0:1]
	global_load_dwordx4 v[180:183], v[18:19], off nt
	global_load_dwordx4 v[184:187], v[18:19], off offset:16 nt
	v_add_u32_e32 v8, s4, v8
	v_add_u32_e32 v6, s5, v6
	v_ashrrev_i32_e32 v7, 31, v6
	v_lshl_add_u64 v[18:19], v[6:7], 4, s[0:1]
	global_load_dwordx4 v[188:191], v[18:19], off nt
	global_load_dwordx4 v[192:195], v[18:19], off offset:16 nt
	v_add_u32_e32 v8, s4, v8
	v_add_u32_e32 v6, s5, v6
	v_ashrrev_i32_e32 v7, 31, v6
	v_lshl_add_u64 v[18:19], v[6:7], 4, s[0:1]
	global_load_dwordx4 v[196:199], v[18:19], off nt
	global_load_dwordx4 v[200:203], v[18:19], off offset:16 nt
	v_add_u32_e32 v8, s4, v8
	v_add_u32_e32 v6, s5, v6
	v_cmp_lt_i32_e32 vcc, s10, v8
	s_waitcnt vmcnt(6)
	v_cvt_pk_bf16_f32 v168, v168, v169
	v_cvt_pk_bf16_f32 v169, v170, v171
	v_cvt_pk_bf16_f32 v170, v176, v177
	v_cvt_pk_bf16_f32 v171, v178, v179
	global_store_dwordx4 v[4:5], v[168:171], off
	v_lshl_add_u64 v[4:5], v[4:5], 0, s[2:3]
	s_or_b64 s[8:9], vcc, s[8:9]
	s_waitcnt vmcnt(5)
	v_cvt_pk_bf16_f32 v180, v180, v181
	v_cvt_pk_bf16_f32 v181, v182, v183
	v_cvt_pk_bf16_f32 v182, v184, v185
	v_cvt_pk_bf16_f32 v183, v186, v187
	global_store_dwordx4 v[4:5], v[180:183], off
	v_lshl_add_u64 v[4:5], v[4:5], 0, s[2:3]
	s_waitcnt vmcnt(4)
	v_cvt_pk_bf16_f32 v188, v188, v189
	v_cvt_pk_bf16_f32 v189, v190, v191
	v_cvt_pk_bf16_f32 v190, v192, v193
	v_cvt_pk_bf16_f32 v191, v194, v195
	global_store_dwordx4 v[4:5], v[188:191], off
	v_lshl_add_u64 v[4:5], v[4:5], 0, s[2:3]
	s_waitcnt vmcnt(3)
	v_cvt_pk_bf16_f32 v196, v196, v197
	v_cvt_pk_bf16_f32 v197, v198, v199
	v_cvt_pk_bf16_f32 v198, v200, v201
	v_cvt_pk_bf16_f32 v199, v202, v203
	global_store_dwordx4 v[4:5], v[196:199], off
	v_lshl_add_u64 v[4:5], v[4:5], 0, s[2:3]
	s_andn2_b64 exec, exec, s[8:9]
	s_cbranch_execnz .LBB0_106

.LBB0_1669:
	v_ashrrev_i32_e32 v5, 31, v4
	v_lshl_add_u64 v[10:11], v[4:5], 4, s[6:7]
	global_load_dwordx4 v[168:171], v[10:11], off nt
	global_load_dwordx4 v[176:179], v[10:11], off offset:16 nt
	v_add_u32_e32 v0, s2, v0
	v_add_u32_e32 v4, s3, v4
	v_ashrrev_i32_e32 v5, 31, v4
	v_lshl_add_u64 v[10:11], v[4:5], 4, s[6:7]
	global_load_dwordx4 v[180:183], v[10:11], off nt
	global_load_dwordx4 v[184:187], v[10:11], off offset:16 nt
	v_add_u32_e32 v0, s2, v0
	v_add_u32_e32 v4, s3, v4
	v_ashrrev_i32_e32 v5, 31, v4
	v_lshl_add_u64 v[10:11], v[4:5], 4, s[6:7]
	global_load_dwordx4 v[188:191], v[10:11], off nt
	global_load_dwordx4 v[192:195], v[10:11], off offset:16 nt
	v_add_u32_e32 v0, s2, v0
	v_add_u32_e32 v4, s3, v4
	v_ashrrev_i32_e32 v5, 31, v4
	v_lshl_add_u64 v[10:11], v[4:5], 4, s[6:7]
	global_load_dwordx4 v[196:199], v[10:11], off nt
	global_load_dwordx4 v[200:203], v[10:11], off offset:16 nt
	v_add_u32_e32 v0, s2, v0
	v_add_u32_e32 v4, s3, v4
	v_cmp_lt_i32_e32 vcc, s28, v0
	s_waitcnt vmcnt(6)
	v_cvt_pk_bf16_f32 v168, v168, v169
	v_cvt_pk_bf16_f32 v169, v170, v171
	v_cvt_pk_bf16_f32 v170, v176, v177
	v_cvt_pk_bf16_f32 v171, v178, v179
	global_store_dwordx4 v[2:3], v[168:171], off
	v_lshl_add_u64 v[2:3], v[2:3], 0, s[0:1]
	s_or_b64 s[10:11], vcc, s[10:11]
	s_waitcnt vmcnt(5)
	v_cvt_pk_bf16_f32 v180, v180, v181
	v_cvt_pk_bf16_f32 v181, v182, v183
	v_cvt_pk_bf16_f32 v182, v184, v185
	v_cvt_pk_bf16_f32 v183, v186, v187
	global_store_dwordx4 v[2:3], v[180:183], off
	v_lshl_add_u64 v[2:3], v[2:3], 0, s[0:1]
	s_waitcnt vmcnt(4)
	v_cvt_pk_bf16_f32 v188, v188, v189
	v_cvt_pk_bf16_f32 v189, v190, v191
	v_cvt_pk_bf16_f32 v190, v192, v193
	v_cvt_pk_bf16_f32 v191, v194, v195
	global_store_dwordx4 v[2:3], v[188:191], off
	v_lshl_add_u64 v[2:3], v[2:3], 0, s[0:1]
	s_waitcnt vmcnt(3)
	v_cvt_pk_bf16_f32 v196, v196, v197
	v_cvt_pk_bf16_f32 v197, v198, v199
	v_cvt_pk_bf16_f32 v198, v200, v201
	v_cvt_pk_bf16_f32 v199, v202, v203
	global_store_dwordx4 v[2:3], v[196:199], off
	v_lshl_add_u64 v[2:3], v[2:3], 0, s[0:1]
	s_andn2_b64 exec, exec, s[10:11]
	s_cbranch_execnz .LBB0_1669
